# residual GEMM: last K-iteration touches the bf16 residual tile lines (cache warm-up for the epilogue loads), counted waits adjusted
# baseline (speedup 1.0000x reference)
.LBB0_637:
	s_add_i32 s47, s24, 2
	s_add_u32 s48, s22, 0x80
	s_addc_u32 s25, s23, 0
	s_add_i32 s50, 0, 0x10000
	s_cmp_eq_u32 s40, s24
	s_cselect_b32 s25, s7, s25
	s_cselect_b32 s24, s6, s48
	v_add_u32_e32 v135, s50, v249
	s_cselect_b32 s49, s21, s46
	s_cselect_b32 s48, s20, s45
	s_add_i32 s51, 0, 0x14000
	ds_read_b128 v[142:145], v135
	ds_read_b128 v[146:149], v135 offset:1024
	ds_read_b128 v[150:153], v135 offset:2048
	ds_read_b128 v[154:157], v135 offset:3072
	v_add_u32_e32 v135, s51, v249
	ds_read_b128 v[158:161], v135
	ds_read_b128 v[162:165], v135 offset:1024
	ds_read_b128 v[166:169], v135 offset:2048
	ds_read_b128 v[170:173], v135 offset:3072
	v_lshl_add_u64 v[174:175], s[22:23], 0, v[138:139]
	s_add_i32 m0, s31, 0xc000
	ds_read_b128 v[182:185], v251
	ds_read_b128 v[186:189], v251 offset:1024
	ds_read_b128 v[190:193], v251 offset:2048
	ds_read_b128 v[194:197], v251 offset:3072
	ds_read_b128 v[198:201], v251 offset:4096
	ds_read_b128 v[202:205], v251 offset:5120
	ds_read_b128 v[206:209], v251 offset:6144
	ds_read_b128 v[210:213], v251 offset:7168
	global_load_lds_dwordx4 v[174:175], off
	v_lshl_add_u64 v[174:175], s[22:23], 0, v[140:141]
	s_add_i32 m0, s31, 0xe000
	s_nop 0
	global_load_lds_dwordx4 v[174:175], off
	s_waitcnt vmcnt(8)
	s_waitcnt lgkmcnt(0)
	s_barrier
	s_setprio 1
	s_waitcnt lgkmcnt(0)
	v_mfma_f32_16x16x32_bf16 v[130:133], v[142:145], v[182:185], v[130:133]
	v_mfma_f32_16x16x32_bf16 v[130:133], v[146:149], v[186:189], v[130:133]
	v_mfma_f32_16x16x32_bf16 v[126:129], v[150:153], v[182:185], v[126:129]
	v_mfma_f32_16x16x32_bf16 v[126:129], v[154:157], v[186:189], v[126:129]
	v_mfma_f32_16x16x32_bf16 v[114:117], v[142:145], v[190:193], v[114:117]
	v_mfma_f32_16x16x32_bf16 v[114:117], v[146:149], v[194:197], v[114:117]
	v_mfma_f32_16x16x32_bf16 v[110:113], v[150:153], v[190:193], v[110:113]
	v_mfma_f32_16x16x32_bf16 v[110:113], v[154:157], v[194:197], v[110:113]
	v_mfma_f32_16x16x32_bf16 v[98:101], v[142:145], v[198:201], v[98:101]
	v_mfma_f32_16x16x32_bf16 v[98:101], v[146:149], v[202:205], v[98:101]
	v_mfma_f32_16x16x32_bf16 v[94:97], v[150:153], v[198:201], v[94:97]
	v_mfma_f32_16x16x32_bf16 v[94:97], v[154:157], v[202:205], v[94:97]
	v_mfma_f32_16x16x32_bf16 v[82:85], v[142:145], v[206:209], v[82:85]
	v_mfma_f32_16x16x32_bf16 v[82:85], v[146:149], v[210:213], v[82:85]
	v_mfma_f32_16x16x32_bf16 v[78:81], v[150:153], v[206:209], v[78:81]
	v_mfma_f32_16x16x32_bf16 v[78:81], v[154:157], v[210:213], v[78:81]
	s_setprio 0
	s_setprio 1
	v_mfma_f32_16x16x32_bf16 v[122:125], v[158:161], v[182:185], v[122:125]
	v_mfma_f32_16x16x32_bf16 v[122:125], v[162:165], v[186:189], v[122:125]
	v_mfma_f32_16x16x32_bf16 v[118:121], v[166:169], v[182:185], v[118:121]
	v_mfma_f32_16x16x32_bf16 v[118:121], v[170:173], v[186:189], v[118:121]
	v_mfma_f32_16x16x32_bf16 v[106:109], v[158:161], v[190:193], v[106:109]
	v_mfma_f32_16x16x32_bf16 v[106:109], v[162:165], v[194:197], v[106:109]
	v_mfma_f32_16x16x32_bf16 v[102:105], v[166:169], v[190:193], v[102:105]
	v_mfma_f32_16x16x32_bf16 v[102:105], v[170:173], v[194:197], v[102:105]
	v_mfma_f32_16x16x32_bf16 v[90:93], v[158:161], v[198:201], v[90:93]
	v_mfma_f32_16x16x32_bf16 v[90:93], v[162:165], v[202:205], v[90:93]
	v_mfma_f32_16x16x32_bf16 v[86:89], v[166:169], v[198:201], v[86:89]
	v_mfma_f32_16x16x32_bf16 v[86:89], v[170:173], v[202:205], v[86:89]
	v_mfma_f32_16x16x32_bf16 v[74:77], v[158:161], v[206:209], v[74:77]
	v_mfma_f32_16x16x32_bf16 v[74:77], v[162:165], v[210:213], v[74:77]
	v_mfma_f32_16x16x32_bf16 v[70:73], v[166:169], v[206:209], v[70:73]
	v_mfma_f32_16x16x32_bf16 v[70:73], v[170:173], v[210:213], v[70:73]
	s_setprio 0
	s_barrier
	s_add_i32 s50, s50, s30
	v_lshl_add_u64 v[174:175], s[48:49], 0, v[0:1]
	s_mov_b32 m0, s50
	ds_read_b128 v[182:185], v251 offset:16384
	ds_read_b128 v[186:189], v251 offset:17408
	ds_read_b128 v[190:193], v251 offset:18432
	ds_read_b128 v[194:197], v251 offset:19456
	ds_read_b128 v[198:201], v251 offset:20480
	ds_read_b128 v[202:205], v251 offset:21504
	ds_read_b128 v[206:209], v251 offset:22528
	ds_read_b128 v[210:213], v251 offset:23552
	global_load_lds_dwordx4 v[174:175], off
	s_add_i32 m0, s50, 0x2000
	v_lshl_add_u64 v[214:215], s[48:49], 0, v[14:15]
	s_add_u32 s48, s48, s10
	s_addc_u32 s49, s49, 0
	s_add_i32 s50, s51, s30
	global_load_lds_dwordx4 v[214:215], off
	v_lshl_add_u64 v[216:217], s[48:49], 0, v[0:1]
	s_mov_b32 m0, s50
	v_lshl_add_u64 v[218:219], s[48:49], 0, v[14:15]
	global_load_lds_dwordx4 v[216:217], off
	s_add_i32 m0, s50, 0x2000
	v_lshl_add_u64 v[220:221], s[24:25], 0, v[0:1]
	global_load_lds_dwordx4 v[218:219], off
	s_mov_b32 m0, s31
	v_lshl_add_u64 v[222:223], s[24:25], 0, v[14:15]
	global_load_lds_dwordx4 v[220:221], off
	s_mov_b32 m0, s34
	s_nop 0
	global_load_lds_dwordx4 v[222:223], off
	s_cmp_ge_u32 s47, s39
	s_cbranch_scc0 .Lrpf_notlast
	v_and_b32_e32 v226, 0xc0, v17
	v_add_u32_e32 v226, v226, v241
	v_lshl_add_u32 v226, s3, 8, v226
	v_and_b32_e32 v228, 0xe0, v250
	v_lshl_or_b32 v228, s2, 8, v228
	v_lshlrev_b32_e32 v228, 1, v228
	v_mov_b32_e32 v227, 0
	v_mov_b32_e32 v229, 0
	v_lshlrev_b64 v[226:227], 11, v[226:227]
	v_lshl_add_u64 v[226:227], v[226:227], 0, v[228:229]
	v_lshl_add_u64 v[226:227], s[84:85], 0, v[226:227]
	s_mov_b64 s[100:101], 0x40000
	global_load_dword v230, v[226:227], off
	global_load_dword v230, v[226:227], off offset:256
	v_lshl_add_u64 v[226:227], v[226:227], 0, s[100:101]
	s_nop 0
	global_load_dword v230, v[226:227], off
	global_load_dword v230, v[226:227], off offset:256
	s_waitcnt vmcnt(12)
	s_branch .Lrpf_wj_s2

.Lrpf_wj_s2:
	s_waitcnt lgkmcnt(0)
	s_barrier
	s_setprio 1
	s_waitcnt lgkmcnt(0)
	v_mfma_f32_16x16x32_bf16 v[66:69], v[142:145], v[182:185], v[66:69]
	v_mfma_f32_16x16x32_bf16 v[66:69], v[146:149], v[186:189], v[66:69]
	v_mfma_f32_16x16x32_bf16 v[62:65], v[150:153], v[182:185], v[62:65]
	v_mfma_f32_16x16x32_bf16 v[62:65], v[154:157], v[186:189], v[62:65]
	v_mfma_f32_16x16x32_bf16 v[50:53], v[142:145], v[190:193], v[50:53]
	v_mfma_f32_16x16x32_bf16 v[50:53], v[146:149], v[194:197], v[50:53]
	v_mfma_f32_16x16x32_bf16 v[46:49], v[150:153], v[190:193], v[46:49]
	v_mfma_f32_16x16x32_bf16 v[46:49], v[154:157], v[194:197], v[46:49]
	v_mfma_f32_16x16x32_bf16 v[34:37], v[142:145], v[198:201], v[34:37]
	v_mfma_f32_16x16x32_bf16 v[34:37], v[146:149], v[202:205], v[34:37]
	v_mfma_f32_16x16x32_bf16 v[30:33], v[150:153], v[198:201], v[30:33]
	v_mfma_f32_16x16x32_bf16 v[30:33], v[154:157], v[202:205], v[30:33]
	v_mfma_f32_16x16x32_bf16 v[18:21], v[142:145], v[206:209], v[18:21]
	v_mfma_f32_16x16x32_bf16 v[18:21], v[146:149], v[210:213], v[18:21]
	v_mfma_f32_16x16x32_bf16 v[10:13], v[150:153], v[206:209], v[10:13]
	v_mfma_f32_16x16x32_bf16 v[10:13], v[154:157], v[210:213], v[10:13]
	s_setprio 0
	s_setprio 1
	v_mfma_f32_16x16x32_bf16 v[58:61], v[158:161], v[182:185], v[58:61]
	v_mfma_f32_16x16x32_bf16 v[58:61], v[162:165], v[186:189], v[58:61]
	v_mfma_f32_16x16x32_bf16 v[54:57], v[166:169], v[182:185], v[54:57]
	v_mfma_f32_16x16x32_bf16 v[54:57], v[170:173], v[186:189], v[54:57]
	v_mfma_f32_16x16x32_bf16 v[42:45], v[158:161], v[190:193], v[42:45]
	v_mfma_f32_16x16x32_bf16 v[42:45], v[162:165], v[194:197], v[42:45]
	v_mfma_f32_16x16x32_bf16 v[38:41], v[166:169], v[190:193], v[38:41]
	v_mfma_f32_16x16x32_bf16 v[38:41], v[170:173], v[194:197], v[38:41]
	v_mfma_f32_16x16x32_bf16 v[26:29], v[158:161], v[198:201], v[26:29]
	v_mfma_f32_16x16x32_bf16 v[26:29], v[162:165], v[202:205], v[26:29]
	v_mfma_f32_16x16x32_bf16 v[22:25], v[166:169], v[198:201], v[22:25]
	v_mfma_f32_16x16x32_bf16 v[22:25], v[170:173], v[202:205], v[22:25]
	v_mfma_f32_16x16x32_bf16 v[6:9], v[158:161], v[206:209], v[6:9]
	v_mfma_f32_16x16x32_bf16 v[6:9], v[162:165], v[210:213], v[6:9]
	v_mfma_f32_16x16x32_bf16 v[2:5], v[166:169], v[206:209], v[2:5]
	v_mfma_f32_16x16x32_bf16 v[2:5], v[170:173], v[210:213], v[2:5]
	s_setprio 0
	s_barrier
	s_add_i32 s48, 0, 0x18000
	v_add_u32_e32 v135, s48, v249
	s_add_i32 s49, 0, 0x1c000
	ds_read_b128 v[142:145], v135
	ds_read_b128 v[146:149], v135 offset:1024
	ds_read_b128 v[150:153], v135 offset:2048
	ds_read_b128 v[154:157], v135 offset:3072
	v_add_u32_e32 v135, s49, v249
	ds_read_b128 v[158:161], v135
	ds_read_b128 v[162:165], v135 offset:1024
	ds_read_b128 v[166:169], v135 offset:2048
	ds_read_b128 v[170:173], v135 offset:3072
	s_add_u32 s24, s24, s10
	s_addc_u32 s25, s25, 0
	s_mov_b32 m0, s35
	v_lshl_add_u64 v[224:225], s[24:25], 0, v[0:1]
	ds_read_b128 v[182:185], v251 offset:32768
	ds_read_b128 v[186:189], v251 offset:33792
	ds_read_b128 v[190:193], v251 offset:34816
	ds_read_b128 v[194:197], v251 offset:35840
	ds_read_b128 v[198:201], v251 offset:36864
	ds_read_b128 v[202:205], v251 offset:37888
	ds_read_b128 v[206:209], v251 offset:38912
	ds_read_b128 v[210:213], v251 offset:39936
	global_load_lds_dwordx4 v[224:225], off
	v_lshl_add_u64 v[224:225], s[24:25], 0, v[14:15]
	s_mov_b32 m0, s36
	s_nop 0
	global_load_lds_dwordx4 v[224:225], off
	s_cmp_ge_u32 s47, s39
	s_cbranch_scc1 .Lrpf_w12_s3
	s_waitcnt vmcnt(8)
	s_branch .Lrpf_wj_s3
.Lrpf_w12_s3:
	s_waitcnt vmcnt(12)
.Lrpf_wj_s3:
	s_waitcnt lgkmcnt(0)
	s_barrier
	s_setprio 1
	s_waitcnt lgkmcnt(0)
	v_mfma_f32_16x16x32_bf16 v[130:133], v[142:145], v[182:185], v[130:133]
	v_mfma_f32_16x16x32_bf16 v[130:133], v[146:149], v[186:189], v[130:133]
	v_mfma_f32_16x16x32_bf16 v[126:129], v[150:153], v[182:185], v[126:129]
	v_mfma_f32_16x16x32_bf16 v[126:129], v[154:157], v[186:189], v[126:129]
	v_mfma_f32_16x16x32_bf16 v[114:117], v[142:145], v[190:193], v[114:117]
	v_mfma_f32_16x16x32_bf16 v[114:117], v[146:149], v[194:197], v[114:117]
	v_mfma_f32_16x16x32_bf16 v[110:113], v[150:153], v[190:193], v[110:113]
	v_mfma_f32_16x16x32_bf16 v[110:113], v[154:157], v[194:197], v[110:113]
	v_mfma_f32_16x16x32_bf16 v[98:101], v[142:145], v[198:201], v[98:101]
	v_mfma_f32_16x16x32_bf16 v[98:101], v[146:149], v[202:205], v[98:101]
	v_mfma_f32_16x16x32_bf16 v[94:97], v[150:153], v[198:201], v[94:97]
	v_mfma_f32_16x16x32_bf16 v[94:97], v[154:157], v[202:205], v[94:97]
	v_mfma_f32_16x16x32_bf16 v[82:85], v[142:145], v[206:209], v[82:85]
	v_mfma_f32_16x16x32_bf16 v[82:85], v[146:149], v[210:213], v[82:85]
	v_mfma_f32_16x16x32_bf16 v[78:81], v[150:153], v[206:209], v[78:81]
	v_mfma_f32_16x16x32_bf16 v[78:81], v[154:157], v[210:213], v[78:81]
	s_setprio 0
	s_setprio 1
	v_mfma_f32_16x16x32_bf16 v[122:125], v[158:161], v[182:185], v[122:125]
	v_mfma_f32_16x16x32_bf16 v[122:125], v[162:165], v[186:189], v[122:125]
	v_mfma_f32_16x16x32_bf16 v[118:121], v[166:169], v[182:185], v[118:121]
	v_mfma_f32_16x16x32_bf16 v[118:121], v[170:173], v[186:189], v[118:121]
	v_mfma_f32_16x16x32_bf16 v[106:109], v[158:161], v[190:193], v[106:109]
	v_mfma_f32_16x16x32_bf16 v[106:109], v[162:165], v[194:197], v[106:109]
	v_mfma_f32_16x16x32_bf16 v[102:105], v[166:169], v[190:193], v[102:105]
	v_mfma_f32_16x16x32_bf16 v[102:105], v[170:173], v[194:197], v[102:105]
	v_mfma_f32_16x16x32_bf16 v[90:93], v[158:161], v[198:201], v[90:93]
	v_mfma_f32_16x16x32_bf16 v[90:93], v[162:165], v[202:205], v[90:93]
	v_mfma_f32_16x16x32_bf16 v[86:89], v[166:169], v[198:201], v[86:89]
	v_mfma_f32_16x16x32_bf16 v[86:89], v[170:173], v[202:205], v[86:89]
	v_mfma_f32_16x16x32_bf16 v[74:77], v[158:161], v[206:209], v[74:77]
	v_mfma_f32_16x16x32_bf16 v[74:77], v[162:165], v[210:213], v[74:77]
	v_mfma_f32_16x16x32_bf16 v[70:73], v[166:169], v[206:209], v[70:73]
	v_mfma_f32_16x16x32_bf16 v[70:73], v[170:173], v[210:213], v[70:73]
	s_setprio 0
	s_barrier
	s_add_i32 s24, s48, s30
	v_lshl_add_u64 v[174:175], v[174:175], 0, s[92:93]
	s_mov_b32 m0, s24
	ds_read_b128 v[182:185], v251 offset:49152
	ds_read_b128 v[186:189], v251 offset:50176
	ds_read_b128 v[190:193], v251 offset:51200
	ds_read_b128 v[194:197], v251 offset:52224
	ds_read_b128 v[198:201], v251 offset:53248
	ds_read_b128 v[202:205], v251 offset:54272
	ds_read_b128 v[206:209], v251 offset:55296
	ds_read_b128 v[210:213], v251 offset:56320
	global_load_lds_dwordx4 v[174:175], off
	v_lshl_add_u64 v[174:175], v[214:215], 0, s[92:93]
	s_add_i32 m0, s24, 0x2000
	s_add_i32 s24, s49, s30
	global_load_lds_dwordx4 v[174:175], off
	v_lshl_add_u64 v[174:175], v[216:217], 0, s[92:93]
	s_mov_b32 m0, s24
	s_nop 0
	global_load_lds_dwordx4 v[174:175], off
	v_lshl_add_u64 v[174:175], v[218:219], 0, s[92:93]
	s_add_i32 m0, s24, 0x2000
	s_nop 0
	global_load_lds_dwordx4 v[174:175], off
	v_lshl_add_u64 v[174:175], v[220:221], 0, s[92:93]
	s_mov_b32 m0, s37
	s_nop 0
	global_load_lds_dwordx4 v[174:175], off
	v_lshl_add_u64 v[174:175], v[222:223], 0, s[92:93]
	s_mov_b32 m0, s38
	s_nop 0
	global_load_lds_dwordx4 v[174:175], off
	s_cmp_ge_u32 s47, s39
	s_cbranch_scc1 .Lrpf_w12_s4
	s_waitcnt vmcnt(8)
	s_branch .Lrpf_wj_s4

.Lrpf_wj_s4:
	s_waitcnt lgkmcnt(0)
	s_barrier
	s_setprio 1
	s_waitcnt lgkmcnt(0)
	v_mfma_f32_16x16x32_bf16 v[66:69], v[142:145], v[182:185], v[66:69]
	v_mfma_f32_16x16x32_bf16 v[66:69], v[146:149], v[186:189], v[66:69]
	v_mfma_f32_16x16x32_bf16 v[62:65], v[150:153], v[182:185], v[62:65]
	v_mfma_f32_16x16x32_bf16 v[62:65], v[154:157], v[186:189], v[62:65]
	v_mfma_f32_16x16x32_bf16 v[50:53], v[142:145], v[190:193], v[50:53]
	v_mfma_f32_16x16x32_bf16 v[50:53], v[146:149], v[194:197], v[50:53]
	v_mfma_f32_16x16x32_bf16 v[46:49], v[150:153], v[190:193], v[46:49]
	v_mfma_f32_16x16x32_bf16 v[46:49], v[154:157], v[194:197], v[46:49]
	v_mfma_f32_16x16x32_bf16 v[34:37], v[142:145], v[198:201], v[34:37]
	v_mfma_f32_16x16x32_bf16 v[34:37], v[146:149], v[202:205], v[34:37]
	v_mfma_f32_16x16x32_bf16 v[30:33], v[150:153], v[198:201], v[30:33]
	v_mfma_f32_16x16x32_bf16 v[30:33], v[154:157], v[202:205], v[30:33]
	v_mfma_f32_16x16x32_bf16 v[18:21], v[142:145], v[206:209], v[18:21]
	v_mfma_f32_16x16x32_bf16 v[18:21], v[146:149], v[210:213], v[18:21]
	v_mfma_f32_16x16x32_bf16 v[10:13], v[150:153], v[206:209], v[10:13]
	v_mfma_f32_16x16x32_bf16 v[10:13], v[154:157], v[210:213], v[10:13]
	s_setprio 0
	s_setprio 1
	v_mfma_f32_16x16x32_bf16 v[58:61], v[158:161], v[182:185], v[58:61]
	v_mfma_f32_16x16x32_bf16 v[58:61], v[162:165], v[186:189], v[58:61]
	v_mfma_f32_16x16x32_bf16 v[54:57], v[166:169], v[182:185], v[54:57]
	v_mfma_f32_16x16x32_bf16 v[54:57], v[170:173], v[186:189], v[54:57]
	v_mfma_f32_16x16x32_bf16 v[42:45], v[158:161], v[190:193], v[42:45]
	v_mfma_f32_16x16x32_bf16 v[42:45], v[162:165], v[194:197], v[42:45]
	v_mfma_f32_16x16x32_bf16 v[38:41], v[166:169], v[190:193], v[38:41]
	v_mfma_f32_16x16x32_bf16 v[38:41], v[170:173], v[194:197], v[38:41]
	v_mfma_f32_16x16x32_bf16 v[26:29], v[158:161], v[198:201], v[26:29]
	v_mfma_f32_16x16x32_bf16 v[26:29], v[162:165], v[202:205], v[26:29]
	v_mfma_f32_16x16x32_bf16 v[22:25], v[166:169], v[198:201], v[22:25]
	v_mfma_f32_16x16x32_bf16 v[22:25], v[170:173], v[202:205], v[22:25]
	v_mfma_f32_16x16x32_bf16 v[6:9], v[158:161], v[206:209], v[6:9]
	v_mfma_f32_16x16x32_bf16 v[6:9], v[162:165], v[210:213], v[6:9]
	v_mfma_f32_16x16x32_bf16 v[2:5], v[166:169], v[206:209], v[2:5]
	v_mfma_f32_16x16x32_bf16 v[2:5], v[170:173], v[210:213], v[2:5]
	s_setprio 0
	s_barrier
	s_add_u32 s22, s22, 0x100
	s_addc_u32 s23, s23, 0
	s_add_u32 s45, s45, 0x100
	s_addc_u32 s46, s46, 0
	s_cmp_ge_u32 s47, s39
	s_mov_b32 s24, s47
	s_cbranch_scc0 .LBB0_637
	s_and_b64 vcc, exec, s[18:19]
	s_cbranch_vccz .LBB0_640
	s_barrier
